# W_in weight-transpose items (main conversion and P0 copies): 32 serialized row loads + gain loads replaced by two batches of 16+16 loads in flight
# speedup vs baseline: 1.0031x; 1.0031x over previous
; #define LAS __attribute__((address_space(3)))
; #define LDS_WAIT() asm volatile("s_waitcnt lgkmcnt(0)" ::: "memory")
; __device__ __forceinline__ void tr_item(const float* W, int ldw, int k0, int n0, bf16_t* WT, int ldt, int drow0, int dk0, LAS float* scr, int lane, const float* kgain = nullptr) {
; #pragma unroll 8
;     for (int i = 0; i < 32; ++i) { const int kk = 2 * i + (lane >> 5); float w = W[(size_t)(k0 + kk) * ldw + n0 + (lane & 31)]; if (kgain) w *= kgain[k0 + kk]; scr[kk * 33 + (lane & 31)] = w; }
;     LDS_WAIT(); asm volatile("" ::: "memory");
; __device__ __forceinline__ void convert_weights(const Args& a, int l, LAS unsigned char* lds, unsigned* ctr, int wave, int lane, int lo, int hi) {
;     ...
;             tr_item(w_in, DIN, kb * 64, n0, WinT, 1024, d, kb * 64, scr, lane, ngain); continue; } r -= I_IN;
.LBB0_713:
	s_mov_b32 s22, 0x9100
	s_mov_b32 s23, 0
	v_mov_b32_e32 v70, v30
	v_mov_b32_e32 v71, v31
	global_load_dword v118, v[70:71], off
	v_lshl_add_u64 v[70:71], v[70:71], 0, s[22:23]
	global_load_dword v119, v[70:71], off
	v_lshl_add_u64 v[70:71], v[70:71], 0, s[22:23]
	global_load_dword v120, v[70:71], off
	v_lshl_add_u64 v[70:71], v[70:71], 0, s[22:23]
	global_load_dword v121, v[70:71], off
	v_lshl_add_u64 v[70:71], v[70:71], 0, s[22:23]
	global_load_dword v122, v[70:71], off
	v_lshl_add_u64 v[70:71], v[70:71], 0, s[22:23]
	global_load_dword v123, v[70:71], off
	v_lshl_add_u64 v[70:71], v[70:71], 0, s[22:23]
	global_load_dword v124, v[70:71], off
	v_lshl_add_u64 v[70:71], v[70:71], 0, s[22:23]
	global_load_dword v125, v[70:71], off
	v_lshl_add_u64 v[70:71], v[70:71], 0, s[22:23]
	global_load_dword v126, v[70:71], off
	v_lshl_add_u64 v[70:71], v[70:71], 0, s[22:23]
	global_load_dword v127, v[70:71], off
	v_lshl_add_u64 v[70:71], v[70:71], 0, s[22:23]
	global_load_dword v128, v[70:71], off
	v_lshl_add_u64 v[70:71], v[70:71], 0, s[22:23]
	global_load_dword v129, v[70:71], off
	v_lshl_add_u64 v[70:71], v[70:71], 0, s[22:23]
	global_load_dword v130, v[70:71], off
	v_lshl_add_u64 v[70:71], v[70:71], 0, s[22:23]
	global_load_dword v131, v[70:71], off
	v_lshl_add_u64 v[70:71], v[70:71], 0, s[22:23]
	global_load_dword v132, v[70:71], off
	v_lshl_add_u64 v[70:71], v[70:71], 0, s[22:23]
	global_load_dword v133, v[70:71], off
	v_lshl_add_u64 v[70:71], v[70:71], 0, s[22:23]
	s_andn2_b64 vcc, exec, s[94:95]
	s_cbranch_vccnz .Ltrin_m_ng0
	global_load_dword v134, v[34:35], off offset:-56
	global_load_dword v135, v[34:35], off offset:-48
	global_load_dword v136, v[34:35], off offset:-40
	global_load_dword v137, v[34:35], off offset:-32
	global_load_dword v138, v[34:35], off offset:-24
	global_load_dword v139, v[34:35], off offset:-16
	global_load_dword v140, v[34:35], off offset:-8
	global_load_dword v141, v[34:35], off
	global_load_dword v142, v[34:35], off offset:8
	global_load_dword v143, v[34:35], off offset:16
	global_load_dword v216, v[34:35], off offset:24
	global_load_dword v217, v[34:35], off offset:32
	global_load_dword v218, v[34:35], off offset:40
	global_load_dword v219, v[34:35], off offset:48
	global_load_dword v220, v[34:35], off offset:56
	global_load_dword v221, v[34:35], off offset:64
	s_waitcnt vmcnt(0)
	v_mul_f32_e32 v118, v118, v134
	v_mul_f32_e32 v119, v119, v135
	v_mul_f32_e32 v120, v120, v136
	v_mul_f32_e32 v121, v121, v137
	v_mul_f32_e32 v122, v122, v138
	v_mul_f32_e32 v123, v123, v139
	v_mul_f32_e32 v124, v124, v140
	v_mul_f32_e32 v125, v125, v141
	v_mul_f32_e32 v126, v126, v142
	v_mul_f32_e32 v127, v127, v143
	v_mul_f32_e32 v128, v128, v216
	v_mul_f32_e32 v129, v129, v217
	v_mul_f32_e32 v130, v130, v218
	v_mul_f32_e32 v131, v131, v219
	v_mul_f32_e32 v132, v132, v220
	v_mul_f32_e32 v133, v133, v221
.Ltrin_m_ng0:
	s_waitcnt vmcnt(0)
	ds_write_b32 v0, v118
	ds_write_b32 v0, v119 offset:264
	ds_write_b32 v0, v120 offset:528
	ds_write_b32 v0, v121 offset:792
	ds_write_b32 v0, v122 offset:1056
	ds_write_b32 v0, v123 offset:1320
	ds_write_b32 v0, v124 offset:1584
	ds_write_b32 v0, v125 offset:1848
	ds_write_b32 v0, v126 offset:2112
	ds_write_b32 v0, v127 offset:2376
	ds_write_b32 v0, v128 offset:2640
	ds_write_b32 v0, v129 offset:2904
	ds_write_b32 v0, v130 offset:3168
	ds_write_b32 v0, v131 offset:3432
	ds_write_b32 v0, v132 offset:3696
	ds_write_b32 v0, v133 offset:3960
	global_load_dword v118, v[70:71], off
	v_lshl_add_u64 v[70:71], v[70:71], 0, s[22:23]
	global_load_dword v119, v[70:71], off
	v_lshl_add_u64 v[70:71], v[70:71], 0, s[22:23]
	global_load_dword v120, v[70:71], off
	v_lshl_add_u64 v[70:71], v[70:71], 0, s[22:23]
	global_load_dword v121, v[70:71], off
	v_lshl_add_u64 v[70:71], v[70:71], 0, s[22:23]
	global_load_dword v122, v[70:71], off
	v_lshl_add_u64 v[70:71], v[70:71], 0, s[22:23]
	global_load_dword v123, v[70:71], off
	v_lshl_add_u64 v[70:71], v[70:71], 0, s[22:23]
	global_load_dword v124, v[70:71], off
	v_lshl_add_u64 v[70:71], v[70:71], 0, s[22:23]
	global_load_dword v125, v[70:71], off
	v_lshl_add_u64 v[70:71], v[70:71], 0, s[22:23]
	global_load_dword v126, v[70:71], off
	v_lshl_add_u64 v[70:71], v[70:71], 0, s[22:23]
	global_load_dword v127, v[70:71], off
	v_lshl_add_u64 v[70:71], v[70:71], 0, s[22:23]
	global_load_dword v128, v[70:71], off
	v_lshl_add_u64 v[70:71], v[70:71], 0, s[22:23]
	global_load_dword v129, v[70:71], off
	v_lshl_add_u64 v[70:71], v[70:71], 0, s[22:23]
	global_load_dword v130, v[70:71], off
	v_lshl_add_u64 v[70:71], v[70:71], 0, s[22:23]
	global_load_dword v131, v[70:71], off
	v_lshl_add_u64 v[70:71], v[70:71], 0, s[22:23]
	global_load_dword v132, v[70:71], off
	v_lshl_add_u64 v[70:71], v[70:71], 0, s[22:23]
	global_load_dword v133, v[70:71], off
	v_lshl_add_u64 v[70:71], v[70:71], 0, s[22:23]
	s_andn2_b64 vcc, exec, s[94:95]
	s_cbranch_vccnz .Ltrin_m_ng1
	global_load_dword v134, v[34:35], off offset:72
	global_load_dword v135, v[34:35], off offset:80
	global_load_dword v136, v[34:35], off offset:88
	global_load_dword v137, v[34:35], off offset:96
	global_load_dword v138, v[34:35], off offset:104
	global_load_dword v139, v[34:35], off offset:112
	global_load_dword v140, v[34:35], off offset:120
	global_load_dword v141, v[34:35], off offset:128
	global_load_dword v142, v[34:35], off offset:136
	global_load_dword v143, v[34:35], off offset:144
	global_load_dword v216, v[34:35], off offset:152
	global_load_dword v217, v[34:35], off offset:160
	global_load_dword v218, v[34:35], off offset:168
	global_load_dword v219, v[34:35], off offset:176
	global_load_dword v220, v[34:35], off offset:184
	global_load_dword v221, v[34:35], off offset:192
	s_waitcnt vmcnt(0)
	v_mul_f32_e32 v118, v118, v134
	v_mul_f32_e32 v119, v119, v135
	v_mul_f32_e32 v120, v120, v136
	v_mul_f32_e32 v121, v121, v137
	v_mul_f32_e32 v122, v122, v138
	v_mul_f32_e32 v123, v123, v139
	v_mul_f32_e32 v124, v124, v140
	v_mul_f32_e32 v125, v125, v141
	v_mul_f32_e32 v126, v126, v142
	v_mul_f32_e32 v127, v127, v143
	v_mul_f32_e32 v128, v128, v216
	v_mul_f32_e32 v129, v129, v217
	v_mul_f32_e32 v130, v130, v218
	v_mul_f32_e32 v131, v131, v219
	v_mul_f32_e32 v132, v132, v220
	v_mul_f32_e32 v133, v133, v221
.Ltrin_m_ng1:
	s_waitcnt vmcnt(0)
	ds_write_b32 v0, v118 offset:4224
	ds_write_b32 v0, v119 offset:4488
	ds_write_b32 v0, v120 offset:4752
	ds_write_b32 v0, v121 offset:5016
	ds_write_b32 v0, v122 offset:5280
	ds_write_b32 v0, v123 offset:5544
	ds_write_b32 v0, v124 offset:5808
	ds_write_b32 v0, v125 offset:6072
	ds_write_b32 v0, v126 offset:6336
	ds_write_b32 v0, v127 offset:6600
	ds_write_b32 v0, v128 offset:6864
	ds_write_b32 v0, v129 offset:7128
	ds_write_b32 v0, v130 offset:7392
	ds_write_b32 v0, v131 offset:7656
	ds_write_b32 v0, v132 offset:7920
	ds_write_b32 v0, v133 offset:8184

; #define LAS __attribute__((address_space(3)))
; #define LDS_WAIT() asm volatile("s_waitcnt lgkmcnt(0)" ::: "memory")
; __device__ __forceinline__ void tr_item(const float* W, int ldw, int k0, int n0, bf16_t* WT, int ldt, int drow0, int dk0, LAS float* scr, int lane, const float* kgain = nullptr) {
; #pragma unroll 8
;     for (int i = 0; i < 32; ++i) { const int kk = 2 * i + (lane >> 5); float w = W[(size_t)(k0 + kk) * ldw + n0 + (lane & 31)]; if (kgain) w *= kgain[k0 + kk]; scr[kk * 33 + (lane & 31)] = w; }
;     LDS_WAIT(); asm volatile("" ::: "memory");
; __device__ __forceinline__ void convert_weights(const Args& a, int l, LAS unsigned char* lds, unsigned* ctr, int wave, int lane, int lo, int hi) {
;     ...
;             tr_item(w_in, DIN, kb * 64, n0, WinT, 1024, d, kb * 64, scr, lane, ngain); continue; } r -= I_IN;
.LBB0_795:
	s_mov_b32 s6, 0x9100
	s_mov_b32 s7, 0
	v_mov_b32_e32 v44, v10
	v_mov_b32_e32 v45, v11
	global_load_dword v118, v[44:45], off
	v_lshl_add_u64 v[44:45], v[44:45], 0, s[6:7]
	global_load_dword v119, v[44:45], off
	v_lshl_add_u64 v[44:45], v[44:45], 0, s[6:7]
	global_load_dword v120, v[44:45], off
	v_lshl_add_u64 v[44:45], v[44:45], 0, s[6:7]
	global_load_dword v121, v[44:45], off
	v_lshl_add_u64 v[44:45], v[44:45], 0, s[6:7]
	global_load_dword v122, v[44:45], off
	v_lshl_add_u64 v[44:45], v[44:45], 0, s[6:7]
	global_load_dword v123, v[44:45], off
	v_lshl_add_u64 v[44:45], v[44:45], 0, s[6:7]
	global_load_dword v124, v[44:45], off
	v_lshl_add_u64 v[44:45], v[44:45], 0, s[6:7]
	global_load_dword v125, v[44:45], off
	v_lshl_add_u64 v[44:45], v[44:45], 0, s[6:7]
	global_load_dword v126, v[44:45], off
	v_lshl_add_u64 v[44:45], v[44:45], 0, s[6:7]
	global_load_dword v127, v[44:45], off
	v_lshl_add_u64 v[44:45], v[44:45], 0, s[6:7]
	global_load_dword v128, v[44:45], off
	v_lshl_add_u64 v[44:45], v[44:45], 0, s[6:7]
	global_load_dword v129, v[44:45], off
	v_lshl_add_u64 v[44:45], v[44:45], 0, s[6:7]
	global_load_dword v130, v[44:45], off
	v_lshl_add_u64 v[44:45], v[44:45], 0, s[6:7]
	global_load_dword v131, v[44:45], off
	v_lshl_add_u64 v[44:45], v[44:45], 0, s[6:7]
	global_load_dword v132, v[44:45], off
	v_lshl_add_u64 v[44:45], v[44:45], 0, s[6:7]
	global_load_dword v133, v[44:45], off
	v_lshl_add_u64 v[44:45], v[44:45], 0, s[6:7]
	s_andn2_b64 vcc, exec, s[94:95]
	s_cbranch_vccnz .Ltrin_p_ng0
	global_load_dword v134, v[14:15], off offset:-56
	global_load_dword v135, v[14:15], off offset:-48
	global_load_dword v136, v[14:15], off offset:-40
	global_load_dword v137, v[14:15], off offset:-32
	global_load_dword v138, v[14:15], off offset:-24
	global_load_dword v139, v[14:15], off offset:-16
	global_load_dword v140, v[14:15], off offset:-8
	global_load_dword v141, v[14:15], off
	global_load_dword v142, v[14:15], off offset:8
	global_load_dword v143, v[14:15], off offset:16
	global_load_dword v216, v[14:15], off offset:24
	global_load_dword v217, v[14:15], off offset:32
	global_load_dword v218, v[14:15], off offset:40
	global_load_dword v219, v[14:15], off offset:48
	global_load_dword v220, v[14:15], off offset:56
	global_load_dword v221, v[14:15], off offset:64
	s_waitcnt vmcnt(0)
	v_mul_f32_e32 v118, v118, v134
	v_mul_f32_e32 v119, v119, v135
	v_mul_f32_e32 v120, v120, v136
	v_mul_f32_e32 v121, v121, v137
	v_mul_f32_e32 v122, v122, v138
	v_mul_f32_e32 v123, v123, v139
	v_mul_f32_e32 v124, v124, v140
	v_mul_f32_e32 v125, v125, v141
	v_mul_f32_e32 v126, v126, v142
	v_mul_f32_e32 v127, v127, v143
	v_mul_f32_e32 v128, v128, v216
	v_mul_f32_e32 v129, v129, v217
	v_mul_f32_e32 v130, v130, v218
	v_mul_f32_e32 v131, v131, v219
	v_mul_f32_e32 v132, v132, v220
	v_mul_f32_e32 v133, v133, v221
.Ltrin_p_ng0:
	s_waitcnt vmcnt(0)
	ds_write_b32 v0, v118
	ds_write_b32 v0, v119 offset:264
	ds_write_b32 v0, v120 offset:528
	ds_write_b32 v0, v121 offset:792
	ds_write_b32 v0, v122 offset:1056
	ds_write_b32 v0, v123 offset:1320
	ds_write_b32 v0, v124 offset:1584
	ds_write_b32 v0, v125 offset:1848
	ds_write_b32 v0, v126 offset:2112
	ds_write_b32 v0, v127 offset:2376
	ds_write_b32 v0, v128 offset:2640
	ds_write_b32 v0, v129 offset:2904
	ds_write_b32 v0, v130 offset:3168
	ds_write_b32 v0, v131 offset:3432
	ds_write_b32 v0, v132 offset:3696
	ds_write_b32 v0, v133 offset:3960
	global_load_dword v118, v[44:45], off
	v_lshl_add_u64 v[44:45], v[44:45], 0, s[6:7]
	global_load_dword v119, v[44:45], off
	v_lshl_add_u64 v[44:45], v[44:45], 0, s[6:7]
	global_load_dword v120, v[44:45], off
	v_lshl_add_u64 v[44:45], v[44:45], 0, s[6:7]
	global_load_dword v121, v[44:45], off
	v_lshl_add_u64 v[44:45], v[44:45], 0, s[6:7]
	global_load_dword v122, v[44:45], off
	v_lshl_add_u64 v[44:45], v[44:45], 0, s[6:7]
	global_load_dword v123, v[44:45], off
	v_lshl_add_u64 v[44:45], v[44:45], 0, s[6:7]
	global_load_dword v124, v[44:45], off
	v_lshl_add_u64 v[44:45], v[44:45], 0, s[6:7]
	global_load_dword v125, v[44:45], off
	v_lshl_add_u64 v[44:45], v[44:45], 0, s[6:7]
	global_load_dword v126, v[44:45], off
	v_lshl_add_u64 v[44:45], v[44:45], 0, s[6:7]
	global_load_dword v127, v[44:45], off
	v_lshl_add_u64 v[44:45], v[44:45], 0, s[6:7]
	global_load_dword v128, v[44:45], off
	v_lshl_add_u64 v[44:45], v[44:45], 0, s[6:7]
	global_load_dword v129, v[44:45], off
	v_lshl_add_u64 v[44:45], v[44:45], 0, s[6:7]
	global_load_dword v130, v[44:45], off
	v_lshl_add_u64 v[44:45], v[44:45], 0, s[6:7]
	global_load_dword v131, v[44:45], off
	v_lshl_add_u64 v[44:45], v[44:45], 0, s[6:7]
	global_load_dword v132, v[44:45], off
	v_lshl_add_u64 v[44:45], v[44:45], 0, s[6:7]
	global_load_dword v133, v[44:45], off
	v_lshl_add_u64 v[44:45], v[44:45], 0, s[6:7]
	s_andn2_b64 vcc, exec, s[94:95]
	s_cbranch_vccnz .Ltrin_p_ng1
	global_load_dword v134, v[14:15], off offset:72
	global_load_dword v135, v[14:15], off offset:80
	global_load_dword v136, v[14:15], off offset:88
	global_load_dword v137, v[14:15], off offset:96
	global_load_dword v138, v[14:15], off offset:104
	global_load_dword v139, v[14:15], off offset:112
	global_load_dword v140, v[14:15], off offset:120
	global_load_dword v141, v[14:15], off offset:128
	global_load_dword v142, v[14:15], off offset:136
	global_load_dword v143, v[14:15], off offset:144
	global_load_dword v216, v[14:15], off offset:152
	global_load_dword v217, v[14:15], off offset:160
	global_load_dword v218, v[14:15], off offset:168
	global_load_dword v219, v[14:15], off offset:176
	global_load_dword v220, v[14:15], off offset:184
	global_load_dword v221, v[14:15], off offset:192
	s_waitcnt vmcnt(0)
	v_mul_f32_e32 v118, v118, v134
	v_mul_f32_e32 v119, v119, v135
	v_mul_f32_e32 v120, v120, v136
	v_mul_f32_e32 v121, v121, v137
	v_mul_f32_e32 v122, v122, v138
	v_mul_f32_e32 v123, v123, v139
	v_mul_f32_e32 v124, v124, v140
	v_mul_f32_e32 v125, v125, v141
	v_mul_f32_e32 v126, v126, v142
	v_mul_f32_e32 v127, v127, v143
	v_mul_f32_e32 v128, v128, v216
	v_mul_f32_e32 v129, v129, v217
	v_mul_f32_e32 v130, v130, v218
	v_mul_f32_e32 v131, v131, v219
	v_mul_f32_e32 v132, v132, v220
	v_mul_f32_e32 v133, v133, v221
